# EpiUp: s_setprio 2 for the younger half (waves 4-7) during the epilogue only, to equalise the VALU-bound epilogue finish times
# baseline (speedup 1.0000x reference)
.LBB0_246:
	s_cmp_lg_u32 s15, 1
	s_cbranch_scc1 .Lepi_noprio
	s_setprio 2

.Lepi_st00:
	s_and_saveexec_b64 s[70:71], s[76:77]
	global_store_dwordx4 v175, v[250:253], s[72:73]
	s_or_b64 exec, exec, s[70:71]
	s_add_u32 s72, s84, 0x16000
	v_pk_mul_f32 v[202:203], v[118:119], v[78:79]
	s_addc_u32 s73, s85, 0
	v_pk_mul_f32 v[204:205], v[120:121], v[80:81]
	v_pk_mul_f32 v[242:243], v[218:219], s[98:99]
	v_pk_mul_f32 v[206:207], v[114:115], v[82:83]
	v_pk_mul_f32 v[244:245], v[220:221], s[98:99]
	v_pk_mul_f32 v[226:227], v[116:117], v[84:85]
	v_pk_mul_f32 v[246:247], v[222:223], s[98:99]
	v_fmac_f32_dpp v202, v118, v26 row_shr:1 row_mask:0xf bank_mask:0xf bound_ctrl:1
	v_pk_mul_f32 v[248:249], v[224:225], s[98:99]
	v_fmac_f32_dpp v203, v119, v27 row_shr:1 row_mask:0xf bank_mask:0xf bound_ctrl:1
	v_exp_f32_e32 v242, v242
	v_fmac_f32_dpp v204, v120, v28 row_shr:1 row_mask:0xf bank_mask:0xf bound_ctrl:1
	v_exp_f32_e32 v243, v243
	v_fmac_f32_dpp v205, v121, v29 row_shr:1 row_mask:0xf bank_mask:0xf bound_ctrl:1
	v_exp_f32_e32 v244, v244
	v_fmac_f32_dpp v206, v114, v74 row_shr:1 row_mask:0xf bank_mask:0xf bound_ctrl:1
	v_exp_f32_e32 v245, v245
	v_fmac_f32_dpp v207, v115, v75 row_shr:1 row_mask:0xf bank_mask:0xf bound_ctrl:1
	v_exp_f32_e32 v246, v246
	v_fmac_f32_dpp v226, v116, v76 row_shr:1 row_mask:0xf bank_mask:0xf bound_ctrl:1
	v_exp_f32_e32 v247, v247
	v_fmac_f32_dpp v227, v117, v77 row_shr:1 row_mask:0xf bank_mask:0xf bound_ctrl:1
	v_exp_f32_e32 v248, v248
	v_fmac_f32_dpp v202, v118, v14 row_shr:2 row_mask:0xf bank_mask:0xf bound_ctrl:1
	v_exp_f32_e32 v249, v249
	v_fmac_f32_dpp v203, v119, v15 row_shr:2 row_mask:0xf bank_mask:0xf bound_ctrl:1
	v_pk_add_f32 v[242:243], v[242:243], s[92:93]
	v_fmac_f32_dpp v204, v120, v16 row_shr:2 row_mask:0xf bank_mask:0xf bound_ctrl:1
	v_pk_add_f32 v[244:245], v[244:245], s[92:93]
	v_fmac_f32_dpp v205, v121, v17 row_shr:2 row_mask:0xf bank_mask:0xf bound_ctrl:1
	v_pk_add_f32 v[246:247], v[246:247], s[92:93]
	v_fmac_f32_dpp v206, v114, v22 row_shr:2 row_mask:0xf bank_mask:0xf bound_ctrl:1
	v_pk_add_f32 v[248:249], v[248:249], s[92:93]
	v_fmac_f32_dpp v207, v115, v23 row_shr:2 row_mask:0xf bank_mask:0xf bound_ctrl:1
	v_rcp_f32_e32 v242, v242
	v_fmac_f32_dpp v226, v116, v24 row_shr:2 row_mask:0xf bank_mask:0xf bound_ctrl:1
	v_rcp_f32_e32 v243, v243
	v_fmac_f32_dpp v227, v117, v25 row_shr:2 row_mask:0xf bank_mask:0xf bound_ctrl:1
	v_rcp_f32_e32 v244, v244
	v_fmac_f32_dpp v202, v126, v154 row_ror:1 row_mask:0xf bank_mask:0xf bound_ctrl:1
	v_rcp_f32_e32 v245, v245
	v_fmac_f32_dpp v203, v127, v155 row_ror:1 row_mask:0xf bank_mask:0xf bound_ctrl:1
	v_rcp_f32_e32 v246, v246
	v_fmac_f32_dpp v204, v128, v156 row_ror:1 row_mask:0xf bank_mask:0xf bound_ctrl:1
	v_rcp_f32_e32 v247, v247
	v_fmac_f32_dpp v205, v129, v157 row_ror:1 row_mask:0xf bank_mask:0xf bound_ctrl:1
	v_rcp_f32_e32 v248, v248
	v_fmac_f32_dpp v206, v122, v158 row_ror:1 row_mask:0xf bank_mask:0xf bound_ctrl:1
	v_rcp_f32_e32 v249, v249
	v_fmac_f32_dpp v207, v123, v159 row_ror:1 row_mask:0xf bank_mask:0xf bound_ctrl:1
	v_pk_mul_f32 v[218:219], v[218:219], v[242:243]
	v_fmac_f32_dpp v226, v124, v160 row_ror:1 row_mask:0xf bank_mask:0xf bound_ctrl:1
	v_pk_mul_f32 v[220:221], v[220:221], v[244:245]
	v_fmac_f32_dpp v227, v125, v161 row_ror:1 row_mask:0xf bank_mask:0xf bound_ctrl:1
	v_pk_mul_f32 v[222:223], v[222:223], v[246:247]
	v_fmac_f32_dpp v202, v126, v182 row_ror:2 row_mask:0xf bank_mask:0xf bound_ctrl:1
	v_pk_mul_f32 v[224:225], v[224:225], v[248:249]
	v_fmac_f32_dpp v203, v127, v183 row_ror:2 row_mask:0xf bank_mask:0xf bound_ctrl:1
	v_pk_mul_f32 v[110:111], v[110:111], v[218:219]
	v_fmac_f32_dpp v204, v128, v184 row_ror:2 row_mask:0xf bank_mask:0xf bound_ctrl:1
	v_pk_mul_f32 v[112:113], v[112:113], v[220:221]
	v_fmac_f32_dpp v205, v129, v185 row_ror:2 row_mask:0xf bank_mask:0xf bound_ctrl:1
	v_pk_mul_f32 v[106:107], v[106:107], v[222:223]
	v_fmac_f32_dpp v206, v122, v190 row_ror:2 row_mask:0xf bank_mask:0xf bound_ctrl:1
	v_pk_mul_f32 v[108:109], v[108:109], v[224:225]
	v_fmac_f32_dpp v207, v123, v191 row_ror:2 row_mask:0xf bank_mask:0xf bound_ctrl:1
	v_cvt_pk_bf16_f32 v250, v110, v111
	v_fmac_f32_dpp v226, v124, v192 row_ror:2 row_mask:0xf bank_mask:0xf bound_ctrl:1
	v_cvt_pk_bf16_f32 v251, v112, v113
	v_fmac_f32_dpp v227, v125, v193 row_ror:2 row_mask:0xf bank_mask:0xf bound_ctrl:1
	v_cvt_pk_bf16_f32 v252, v106, v107
	v_cvt_pk_bf16_f32 v253, v108, v109
	global_store_dwordx4 v175, v[250:253], s[72:73]
	s_add_u32 s72, s84, 0x2c000
	v_pk_mul_f32 v[218:219], v[134:135], v[78:79]
	s_addc_u32 s73, s85, 0
	v_pk_mul_f32 v[220:221], v[136:137], v[80:81]
	v_pk_mul_f32 v[242:243], v[202:203], s[98:99]
	v_pk_mul_f32 v[222:223], v[130:131], v[82:83]
	v_pk_mul_f32 v[244:245], v[204:205], s[98:99]
	v_pk_mul_f32 v[224:225], v[132:133], v[84:85]
	v_pk_mul_f32 v[246:247], v[206:207], s[98:99]
	v_fmac_f32_dpp v218, v134, v26 row_shr:1 row_mask:0xf bank_mask:0xf bound_ctrl:1
	v_pk_mul_f32 v[248:249], v[226:227], s[98:99]
	v_fmac_f32_dpp v219, v135, v27 row_shr:1 row_mask:0xf bank_mask:0xf bound_ctrl:1
	v_exp_f32_e32 v242, v242
	v_fmac_f32_dpp v220, v136, v28 row_shr:1 row_mask:0xf bank_mask:0xf bound_ctrl:1
	v_exp_f32_e32 v243, v243
	v_fmac_f32_dpp v221, v137, v29 row_shr:1 row_mask:0xf bank_mask:0xf bound_ctrl:1
	v_exp_f32_e32 v244, v244
	v_fmac_f32_dpp v222, v130, v74 row_shr:1 row_mask:0xf bank_mask:0xf bound_ctrl:1
	v_exp_f32_e32 v245, v245
	v_fmac_f32_dpp v223, v131, v75 row_shr:1 row_mask:0xf bank_mask:0xf bound_ctrl:1
	v_exp_f32_e32 v246, v246
	v_fmac_f32_dpp v224, v132, v76 row_shr:1 row_mask:0xf bank_mask:0xf bound_ctrl:1
	v_exp_f32_e32 v247, v247
	v_fmac_f32_dpp v225, v133, v77 row_shr:1 row_mask:0xf bank_mask:0xf bound_ctrl:1
	v_exp_f32_e32 v248, v248
	v_fmac_f32_dpp v218, v134, v14 row_shr:2 row_mask:0xf bank_mask:0xf bound_ctrl:1
	v_exp_f32_e32 v249, v249
	v_fmac_f32_dpp v219, v135, v15 row_shr:2 row_mask:0xf bank_mask:0xf bound_ctrl:1
	v_pk_add_f32 v[242:243], v[242:243], s[92:93]
	v_fmac_f32_dpp v220, v136, v16 row_shr:2 row_mask:0xf bank_mask:0xf bound_ctrl:1
	v_pk_add_f32 v[244:245], v[244:245], s[92:93]
	v_fmac_f32_dpp v221, v137, v17 row_shr:2 row_mask:0xf bank_mask:0xf bound_ctrl:1
	v_pk_add_f32 v[246:247], v[246:247], s[92:93]
	v_fmac_f32_dpp v222, v130, v22 row_shr:2 row_mask:0xf bank_mask:0xf bound_ctrl:1
	v_pk_add_f32 v[248:249], v[248:249], s[92:93]
	v_fmac_f32_dpp v223, v131, v23 row_shr:2 row_mask:0xf bank_mask:0xf bound_ctrl:1
	v_rcp_f32_e32 v242, v242
	v_fmac_f32_dpp v224, v132, v24 row_shr:2 row_mask:0xf bank_mask:0xf bound_ctrl:1
	v_rcp_f32_e32 v243, v243
	v_fmac_f32_dpp v225, v133, v25 row_shr:2 row_mask:0xf bank_mask:0xf bound_ctrl:1
	v_rcp_f32_e32 v244, v244
	v_fmac_f32_dpp v218, v118, v154 row_ror:1 row_mask:0xf bank_mask:0xf bound_ctrl:1
	v_rcp_f32_e32 v245, v245
	v_fmac_f32_dpp v219, v119, v155 row_ror:1 row_mask:0xf bank_mask:0xf bound_ctrl:1
	v_rcp_f32_e32 v246, v246
	v_fmac_f32_dpp v220, v120, v156 row_ror:1 row_mask:0xf bank_mask:0xf bound_ctrl:1
	v_rcp_f32_e32 v247, v247
	v_fmac_f32_dpp v221, v121, v157 row_ror:1 row_mask:0xf bank_mask:0xf bound_ctrl:1
	v_rcp_f32_e32 v248, v248
	v_fmac_f32_dpp v222, v114, v158 row_ror:1 row_mask:0xf bank_mask:0xf bound_ctrl:1
	v_rcp_f32_e32 v249, v249
	v_fmac_f32_dpp v223, v115, v159 row_ror:1 row_mask:0xf bank_mask:0xf bound_ctrl:1
	v_pk_mul_f32 v[202:203], v[202:203], v[242:243]
	v_fmac_f32_dpp v224, v116, v160 row_ror:1 row_mask:0xf bank_mask:0xf bound_ctrl:1
	v_pk_mul_f32 v[204:205], v[204:205], v[244:245]
	v_fmac_f32_dpp v225, v117, v161 row_ror:1 row_mask:0xf bank_mask:0xf bound_ctrl:1
	v_pk_mul_f32 v[206:207], v[206:207], v[246:247]
	v_fmac_f32_dpp v218, v118, v182 row_ror:2 row_mask:0xf bank_mask:0xf bound_ctrl:1
	v_pk_mul_f32 v[226:227], v[226:227], v[248:249]
	v_fmac_f32_dpp v219, v119, v183 row_ror:2 row_mask:0xf bank_mask:0xf bound_ctrl:1
	v_pk_mul_f32 v[102:103], v[102:103], v[202:203]
	v_fmac_f32_dpp v220, v120, v184 row_ror:2 row_mask:0xf bank_mask:0xf bound_ctrl:1
	v_pk_mul_f32 v[104:105], v[104:105], v[204:205]
	v_fmac_f32_dpp v221, v121, v185 row_ror:2 row_mask:0xf bank_mask:0xf bound_ctrl:1
	v_pk_mul_f32 v[98:99], v[98:99], v[206:207]
	v_fmac_f32_dpp v222, v114, v190 row_ror:2 row_mask:0xf bank_mask:0xf bound_ctrl:1
	v_pk_mul_f32 v[100:101], v[100:101], v[226:227]
	v_fmac_f32_dpp v223, v115, v191 row_ror:2 row_mask:0xf bank_mask:0xf bound_ctrl:1
	v_cvt_pk_bf16_f32 v250, v102, v103
	v_fmac_f32_dpp v224, v116, v192 row_ror:2 row_mask:0xf bank_mask:0xf bound_ctrl:1
	v_cvt_pk_bf16_f32 v251, v104, v105
	v_fmac_f32_dpp v225, v117, v193 row_ror:2 row_mask:0xf bank_mask:0xf bound_ctrl:1
	v_cvt_pk_bf16_f32 v252, v98, v99
	v_cvt_pk_bf16_f32 v253, v100, v101
	global_store_dwordx4 v175, v[250:253], s[72:73]
	s_add_u32 s72, s84, 0x42000
	v_pk_mul_f32 v[202:203], v[70:71], v[78:79]
	s_addc_u32 s73, s85, 0
	v_pk_mul_f32 v[204:205], v[72:73], v[80:81]
	v_pk_mul_f32 v[242:243], v[218:219], s[98:99]
	v_pk_mul_f32 v[206:207], v[66:67], v[82:83]
	v_pk_mul_f32 v[244:245], v[220:221], s[98:99]
	v_pk_mul_f32 v[226:227], v[68:69], v[84:85]
	v_pk_mul_f32 v[246:247], v[222:223], s[98:99]
	v_fmac_f32_dpp v202, v70, v26 row_shr:1 row_mask:0xf bank_mask:0xf bound_ctrl:1
	v_pk_mul_f32 v[248:249], v[224:225], s[98:99]
	v_fmac_f32_dpp v203, v71, v27 row_shr:1 row_mask:0xf bank_mask:0xf bound_ctrl:1
	v_exp_f32_e32 v242, v242
	v_fmac_f32_dpp v204, v72, v28 row_shr:1 row_mask:0xf bank_mask:0xf bound_ctrl:1
	v_exp_f32_e32 v243, v243
	v_fmac_f32_dpp v205, v73, v29 row_shr:1 row_mask:0xf bank_mask:0xf bound_ctrl:1
	v_exp_f32_e32 v244, v244
	v_fmac_f32_dpp v206, v66, v74 row_shr:1 row_mask:0xf bank_mask:0xf bound_ctrl:1
	v_exp_f32_e32 v245, v245
	v_fmac_f32_dpp v207, v67, v75 row_shr:1 row_mask:0xf bank_mask:0xf bound_ctrl:1
	v_exp_f32_e32 v246, v246
	v_fmac_f32_dpp v226, v68, v76 row_shr:1 row_mask:0xf bank_mask:0xf bound_ctrl:1
	v_exp_f32_e32 v247, v247
	v_fmac_f32_dpp v227, v69, v77 row_shr:1 row_mask:0xf bank_mask:0xf bound_ctrl:1
	v_exp_f32_e32 v248, v248
	v_fmac_f32_dpp v202, v70, v14 row_shr:2 row_mask:0xf bank_mask:0xf bound_ctrl:1
	v_exp_f32_e32 v249, v249
	v_fmac_f32_dpp v203, v71, v15 row_shr:2 row_mask:0xf bank_mask:0xf bound_ctrl:1
	v_pk_add_f32 v[242:243], v[242:243], s[92:93]
	v_fmac_f32_dpp v204, v72, v16 row_shr:2 row_mask:0xf bank_mask:0xf bound_ctrl:1
	v_pk_add_f32 v[244:245], v[244:245], s[92:93]
	v_fmac_f32_dpp v205, v73, v17 row_shr:2 row_mask:0xf bank_mask:0xf bound_ctrl:1
	v_pk_add_f32 v[246:247], v[246:247], s[92:93]
	v_fmac_f32_dpp v206, v66, v22 row_shr:2 row_mask:0xf bank_mask:0xf bound_ctrl:1
	v_pk_add_f32 v[248:249], v[248:249], s[92:93]
	v_fmac_f32_dpp v207, v67, v23 row_shr:2 row_mask:0xf bank_mask:0xf bound_ctrl:1
	v_rcp_f32_e32 v242, v242
	v_fmac_f32_dpp v226, v68, v24 row_shr:2 row_mask:0xf bank_mask:0xf bound_ctrl:1
	v_rcp_f32_e32 v243, v243
	v_fmac_f32_dpp v227, v69, v25 row_shr:2 row_mask:0xf bank_mask:0xf bound_ctrl:1
	v_rcp_f32_e32 v244, v244
	v_fmac_f32_dpp v202, v210, v154 row_ror:1 row_mask:0xf bank_mask:0xf bound_ctrl:1
	v_rcp_f32_e32 v245, v245
	v_fmac_f32_dpp v203, v211, v155 row_ror:1 row_mask:0xf bank_mask:0xf bound_ctrl:1
	v_rcp_f32_e32 v246, v246
	v_fmac_f32_dpp v204, v212, v156 row_ror:1 row_mask:0xf bank_mask:0xf bound_ctrl:1
	v_rcp_f32_e32 v247, v247
	v_fmac_f32_dpp v205, v213, v157 row_ror:1 row_mask:0xf bank_mask:0xf bound_ctrl:1
	v_rcp_f32_e32 v248, v248
	v_fmac_f32_dpp v206, v214, v158 row_ror:1 row_mask:0xf bank_mask:0xf bound_ctrl:1
	v_rcp_f32_e32 v249, v249
	v_fmac_f32_dpp v207, v215, v159 row_ror:1 row_mask:0xf bank_mask:0xf bound_ctrl:1
	v_pk_mul_f32 v[218:219], v[218:219], v[242:243]
	v_fmac_f32_dpp v226, v216, v160 row_ror:1 row_mask:0xf bank_mask:0xf bound_ctrl:1
	v_pk_mul_f32 v[220:221], v[220:221], v[244:245]
	v_fmac_f32_dpp v227, v217, v161 row_ror:1 row_mask:0xf bank_mask:0xf bound_ctrl:1
	v_pk_mul_f32 v[222:223], v[222:223], v[246:247]
	v_fmac_f32_dpp v202, v210, v182 row_ror:2 row_mask:0xf bank_mask:0xf bound_ctrl:1
	v_pk_mul_f32 v[224:225], v[224:225], v[248:249]
	v_fmac_f32_dpp v203, v211, v183 row_ror:2 row_mask:0xf bank_mask:0xf bound_ctrl:1
	v_pk_mul_f32 v[94:95], v[94:95], v[218:219]
	v_fmac_f32_dpp v204, v212, v184 row_ror:2 row_mask:0xf bank_mask:0xf bound_ctrl:1
	v_pk_mul_f32 v[96:97], v[96:97], v[220:221]
	v_fmac_f32_dpp v205, v213, v185 row_ror:2 row_mask:0xf bank_mask:0xf bound_ctrl:1
	v_pk_mul_f32 v[90:91], v[90:91], v[222:223]
	v_fmac_f32_dpp v206, v214, v190 row_ror:2 row_mask:0xf bank_mask:0xf bound_ctrl:1
	v_pk_mul_f32 v[92:93], v[92:93], v[224:225]
	v_fmac_f32_dpp v207, v215, v191 row_ror:2 row_mask:0xf bank_mask:0xf bound_ctrl:1
	v_cvt_pk_bf16_f32 v250, v94, v95
	v_fmac_f32_dpp v226, v216, v192 row_ror:2 row_mask:0xf bank_mask:0xf bound_ctrl:1
	v_cvt_pk_bf16_f32 v251, v96, v97
	v_fmac_f32_dpp v227, v217, v193 row_ror:2 row_mask:0xf bank_mask:0xf bound_ctrl:1
	v_cvt_pk_bf16_f32 v252, v90, v91
	v_cvt_pk_bf16_f32 v253, v92, v93
	global_store_dwordx4 v175, v[250:253], s[72:73]
	s_add_u32 s72, s84, 0xb0000
	v_pk_mul_f32 v[218:219], v[62:63], v[78:79]
	s_addc_u32 s73, s85, 0
	v_pk_mul_f32 v[220:221], v[64:65], v[80:81]
	v_pk_mul_f32 v[242:243], v[202:203], s[98:99]
	v_pk_mul_f32 v[222:223], v[54:55], v[82:83]
	v_pk_mul_f32 v[244:245], v[204:205], s[98:99]
	v_pk_mul_f32 v[224:225], v[56:57], v[84:85]
	v_pk_mul_f32 v[246:247], v[206:207], s[98:99]
	v_fmac_f32_dpp v218, v62, v26 row_shr:1 row_mask:0xf bank_mask:0xf bound_ctrl:1
	v_pk_mul_f32 v[248:249], v[226:227], s[98:99]
	v_fmac_f32_dpp v219, v63, v27 row_shr:1 row_mask:0xf bank_mask:0xf bound_ctrl:1
	v_exp_f32_e32 v242, v242
	v_fmac_f32_dpp v220, v64, v28 row_shr:1 row_mask:0xf bank_mask:0xf bound_ctrl:1
	v_exp_f32_e32 v243, v243
	v_fmac_f32_dpp v221, v65, v29 row_shr:1 row_mask:0xf bank_mask:0xf bound_ctrl:1
	v_exp_f32_e32 v244, v244
	v_fmac_f32_dpp v222, v54, v74 row_shr:1 row_mask:0xf bank_mask:0xf bound_ctrl:1
	v_exp_f32_e32 v245, v245
	v_fmac_f32_dpp v223, v55, v75 row_shr:1 row_mask:0xf bank_mask:0xf bound_ctrl:1
	v_exp_f32_e32 v246, v246
	v_fmac_f32_dpp v224, v56, v76 row_shr:1 row_mask:0xf bank_mask:0xf bound_ctrl:1
	v_exp_f32_e32 v247, v247
	v_fmac_f32_dpp v225, v57, v77 row_shr:1 row_mask:0xf bank_mask:0xf bound_ctrl:1
	v_exp_f32_e32 v248, v248
	v_fmac_f32_dpp v218, v62, v14 row_shr:2 row_mask:0xf bank_mask:0xf bound_ctrl:1
	v_exp_f32_e32 v249, v249
	v_fmac_f32_dpp v219, v63, v15 row_shr:2 row_mask:0xf bank_mask:0xf bound_ctrl:1
	v_pk_add_f32 v[242:243], v[242:243], s[92:93]
	v_fmac_f32_dpp v220, v64, v16 row_shr:2 row_mask:0xf bank_mask:0xf bound_ctrl:1
	v_pk_add_f32 v[244:245], v[244:245], s[92:93]
	v_fmac_f32_dpp v221, v65, v17 row_shr:2 row_mask:0xf bank_mask:0xf bound_ctrl:1
	v_pk_add_f32 v[246:247], v[246:247], s[92:93]
	v_fmac_f32_dpp v222, v54, v22 row_shr:2 row_mask:0xf bank_mask:0xf bound_ctrl:1
	v_pk_add_f32 v[248:249], v[248:249], s[92:93]
	v_fmac_f32_dpp v223, v55, v23 row_shr:2 row_mask:0xf bank_mask:0xf bound_ctrl:1
	v_rcp_f32_e32 v242, v242
	v_fmac_f32_dpp v224, v56, v24 row_shr:2 row_mask:0xf bank_mask:0xf bound_ctrl:1
	v_rcp_f32_e32 v243, v243
	v_fmac_f32_dpp v225, v57, v25 row_shr:2 row_mask:0xf bank_mask:0xf bound_ctrl:1
	v_rcp_f32_e32 v244, v244
	v_fmac_f32_dpp v218, v70, v154 row_ror:1 row_mask:0xf bank_mask:0xf bound_ctrl:1
	v_rcp_f32_e32 v245, v245
	v_fmac_f32_dpp v219, v71, v155 row_ror:1 row_mask:0xf bank_mask:0xf bound_ctrl:1
	v_rcp_f32_e32 v246, v246
	v_fmac_f32_dpp v220, v72, v156 row_ror:1 row_mask:0xf bank_mask:0xf bound_ctrl:1
	v_rcp_f32_e32 v247, v247
	v_fmac_f32_dpp v221, v73, v157 row_ror:1 row_mask:0xf bank_mask:0xf bound_ctrl:1
	v_rcp_f32_e32 v248, v248
	v_fmac_f32_dpp v222, v66, v158 row_ror:1 row_mask:0xf bank_mask:0xf bound_ctrl:1
	v_rcp_f32_e32 v249, v249
	v_fmac_f32_dpp v223, v67, v159 row_ror:1 row_mask:0xf bank_mask:0xf bound_ctrl:1
	v_pk_mul_f32 v[202:203], v[202:203], v[242:243]
	v_fmac_f32_dpp v224, v68, v160 row_ror:1 row_mask:0xf bank_mask:0xf bound_ctrl:1
	v_pk_mul_f32 v[204:205], v[204:205], v[244:245]
	v_fmac_f32_dpp v225, v69, v161 row_ror:1 row_mask:0xf bank_mask:0xf bound_ctrl:1
	v_pk_mul_f32 v[206:207], v[206:207], v[246:247]
	v_fmac_f32_dpp v218, v70, v182 row_ror:2 row_mask:0xf bank_mask:0xf bound_ctrl:1
	v_pk_mul_f32 v[226:227], v[226:227], v[248:249]
	v_fmac_f32_dpp v219, v71, v183 row_ror:2 row_mask:0xf bank_mask:0xf bound_ctrl:1
	v_pk_mul_f32 v[50:51], v[50:51], v[202:203]
	v_fmac_f32_dpp v220, v72, v184 row_ror:2 row_mask:0xf bank_mask:0xf bound_ctrl:1
	v_pk_mul_f32 v[52:53], v[52:53], v[204:205]
	v_fmac_f32_dpp v221, v73, v185 row_ror:2 row_mask:0xf bank_mask:0xf bound_ctrl:1
	v_pk_mul_f32 v[46:47], v[46:47], v[206:207]
	v_fmac_f32_dpp v222, v66, v190 row_ror:2 row_mask:0xf bank_mask:0xf bound_ctrl:1
	v_pk_mul_f32 v[48:49], v[48:49], v[226:227]
	v_fmac_f32_dpp v223, v67, v191 row_ror:2 row_mask:0xf bank_mask:0xf bound_ctrl:1
	v_cvt_pk_bf16_f32 v250, v50, v51
	v_fmac_f32_dpp v224, v68, v192 row_ror:2 row_mask:0xf bank_mask:0xf bound_ctrl:1
	v_cvt_pk_bf16_f32 v251, v52, v53
	v_fmac_f32_dpp v225, v69, v193 row_ror:2 row_mask:0xf bank_mask:0xf bound_ctrl:1
	v_cvt_pk_bf16_f32 v252, v46, v47
	v_cvt_pk_bf16_f32 v253, v48, v49
	global_store_dwordx4 v175, v[250:253], s[72:73]
	s_add_u32 s72, s84, 0xc6000
	v_pk_mul_f32 v[202:203], v[42:43], v[78:79]
	s_addc_u32 s73, s85, 0
	v_pk_mul_f32 v[204:205], v[44:45], v[80:81]
	v_pk_mul_f32 v[242:243], v[218:219], s[98:99]
	v_pk_mul_f32 v[206:207], v[38:39], v[82:83]
	v_pk_mul_f32 v[244:245], v[220:221], s[98:99]
	v_pk_mul_f32 v[226:227], v[40:41], v[84:85]
	v_pk_mul_f32 v[246:247], v[222:223], s[98:99]
	v_fmac_f32_dpp v202, v42, v26 row_shr:1 row_mask:0xf bank_mask:0xf bound_ctrl:1
	v_pk_mul_f32 v[248:249], v[224:225], s[98:99]
	v_fmac_f32_dpp v203, v43, v27 row_shr:1 row_mask:0xf bank_mask:0xf bound_ctrl:1
	v_exp_f32_e32 v242, v242
	v_fmac_f32_dpp v204, v44, v28 row_shr:1 row_mask:0xf bank_mask:0xf bound_ctrl:1
	v_exp_f32_e32 v243, v243
	v_fmac_f32_dpp v205, v45, v29 row_shr:1 row_mask:0xf bank_mask:0xf bound_ctrl:1
	v_exp_f32_e32 v244, v244
	v_fmac_f32_dpp v206, v38, v74 row_shr:1 row_mask:0xf bank_mask:0xf bound_ctrl:1
	v_exp_f32_e32 v245, v245
	v_fmac_f32_dpp v207, v39, v75 row_shr:1 row_mask:0xf bank_mask:0xf bound_ctrl:1
	v_exp_f32_e32 v246, v246
	v_fmac_f32_dpp v226, v40, v76 row_shr:1 row_mask:0xf bank_mask:0xf bound_ctrl:1
	v_exp_f32_e32 v247, v247
	v_fmac_f32_dpp v227, v41, v77 row_shr:1 row_mask:0xf bank_mask:0xf bound_ctrl:1
	v_exp_f32_e32 v248, v248
	v_fmac_f32_dpp v202, v42, v14 row_shr:2 row_mask:0xf bank_mask:0xf bound_ctrl:1
	v_exp_f32_e32 v249, v249
	v_fmac_f32_dpp v203, v43, v15 row_shr:2 row_mask:0xf bank_mask:0xf bound_ctrl:1
	v_pk_add_f32 v[242:243], v[242:243], s[92:93]
	v_fmac_f32_dpp v204, v44, v16 row_shr:2 row_mask:0xf bank_mask:0xf bound_ctrl:1
	v_pk_add_f32 v[244:245], v[244:245], s[92:93]
	v_fmac_f32_dpp v205, v45, v17 row_shr:2 row_mask:0xf bank_mask:0xf bound_ctrl:1
	v_pk_add_f32 v[246:247], v[246:247], s[92:93]
	v_fmac_f32_dpp v206, v38, v22 row_shr:2 row_mask:0xf bank_mask:0xf bound_ctrl:1
	v_pk_add_f32 v[248:249], v[248:249], s[92:93]
	v_fmac_f32_dpp v207, v39, v23 row_shr:2 row_mask:0xf bank_mask:0xf bound_ctrl:1
	v_rcp_f32_e32 v242, v242
	v_fmac_f32_dpp v226, v40, v24 row_shr:2 row_mask:0xf bank_mask:0xf bound_ctrl:1
	v_rcp_f32_e32 v243, v243
	v_fmac_f32_dpp v227, v41, v25 row_shr:2 row_mask:0xf bank_mask:0xf bound_ctrl:1
	v_rcp_f32_e32 v244, v244
	v_fmac_f32_dpp v202, v62, v154 row_ror:1 row_mask:0xf bank_mask:0xf bound_ctrl:1
	v_rcp_f32_e32 v245, v245
	v_fmac_f32_dpp v203, v63, v155 row_ror:1 row_mask:0xf bank_mask:0xf bound_ctrl:1
	v_rcp_f32_e32 v246, v246
	v_fmac_f32_dpp v204, v64, v156 row_ror:1 row_mask:0xf bank_mask:0xf bound_ctrl:1
	v_rcp_f32_e32 v247, v247
	v_fmac_f32_dpp v205, v65, v157 row_ror:1 row_mask:0xf bank_mask:0xf bound_ctrl:1
	v_rcp_f32_e32 v248, v248
	v_fmac_f32_dpp v206, v54, v158 row_ror:1 row_mask:0xf bank_mask:0xf bound_ctrl:1
	v_rcp_f32_e32 v249, v249
	v_fmac_f32_dpp v207, v55, v159 row_ror:1 row_mask:0xf bank_mask:0xf bound_ctrl:1
	v_pk_mul_f32 v[218:219], v[218:219], v[242:243]
	v_fmac_f32_dpp v226, v56, v160 row_ror:1 row_mask:0xf bank_mask:0xf bound_ctrl:1
	v_pk_mul_f32 v[220:221], v[220:221], v[244:245]
	v_fmac_f32_dpp v227, v57, v161 row_ror:1 row_mask:0xf bank_mask:0xf bound_ctrl:1
	v_pk_mul_f32 v[222:223], v[222:223], v[246:247]
	v_fmac_f32_dpp v202, v62, v182 row_ror:2 row_mask:0xf bank_mask:0xf bound_ctrl:1
	v_pk_mul_f32 v[224:225], v[224:225], v[248:249]
	v_fmac_f32_dpp v203, v63, v183 row_ror:2 row_mask:0xf bank_mask:0xf bound_ctrl:1
	v_pk_mul_f32 v[34:35], v[34:35], v[218:219]
	v_fmac_f32_dpp v204, v64, v184 row_ror:2 row_mask:0xf bank_mask:0xf bound_ctrl:1
	v_pk_mul_f32 v[36:37], v[36:37], v[220:221]
	v_fmac_f32_dpp v205, v65, v185 row_ror:2 row_mask:0xf bank_mask:0xf bound_ctrl:1
	v_pk_mul_f32 v[30:31], v[30:31], v[222:223]
	v_fmac_f32_dpp v206, v54, v190 row_ror:2 row_mask:0xf bank_mask:0xf bound_ctrl:1
	v_pk_mul_f32 v[32:33], v[32:33], v[224:225]
	v_fmac_f32_dpp v207, v55, v191 row_ror:2 row_mask:0xf bank_mask:0xf bound_ctrl:1
	v_cvt_pk_bf16_f32 v250, v34, v35
	v_fmac_f32_dpp v226, v56, v192 row_ror:2 row_mask:0xf bank_mask:0xf bound_ctrl:1
	v_cvt_pk_bf16_f32 v251, v36, v37
	v_fmac_f32_dpp v227, v57, v193 row_ror:2 row_mask:0xf bank_mask:0xf bound_ctrl:1
	v_cvt_pk_bf16_f32 v252, v30, v31
	v_cvt_pk_bf16_f32 v253, v32, v33
	global_store_dwordx4 v175, v[250:253], s[72:73]
	s_add_u32 s72, s84, 0xdc000
	v_pk_mul_f32 v[218:219], v[86:87], v[78:79]
	s_addc_u32 s73, s85, 0
	v_pk_mul_f32 v[220:221], v[88:89], v[80:81]
	v_pk_mul_f32 v[242:243], v[202:203], s[98:99]
	v_pk_mul_f32 v[222:223], v[146:147], v[82:83]
	v_pk_mul_f32 v[244:245], v[204:205], s[98:99]
	v_pk_mul_f32 v[224:225], v[148:149], v[84:85]
	v_pk_mul_f32 v[246:247], v[206:207], s[98:99]
	v_fmac_f32_dpp v218, v86, v26 row_shr:1 row_mask:0xf bank_mask:0xf bound_ctrl:1
	v_pk_mul_f32 v[248:249], v[226:227], s[98:99]
	v_fmac_f32_dpp v219, v87, v27 row_shr:1 row_mask:0xf bank_mask:0xf bound_ctrl:1
	v_exp_f32_e32 v242, v242
	v_fmac_f32_dpp v220, v88, v28 row_shr:1 row_mask:0xf bank_mask:0xf bound_ctrl:1
	v_exp_f32_e32 v243, v243
	v_fmac_f32_dpp v221, v89, v29 row_shr:1 row_mask:0xf bank_mask:0xf bound_ctrl:1
	v_exp_f32_e32 v244, v244
	v_fmac_f32_dpp v222, v146, v74 row_shr:1 row_mask:0xf bank_mask:0xf bound_ctrl:1
	v_exp_f32_e32 v245, v245
	v_fmac_f32_dpp v223, v147, v75 row_shr:1 row_mask:0xf bank_mask:0xf bound_ctrl:1
	v_exp_f32_e32 v246, v246
	v_fmac_f32_dpp v224, v148, v76 row_shr:1 row_mask:0xf bank_mask:0xf bound_ctrl:1
	v_exp_f32_e32 v247, v247
	v_fmac_f32_dpp v225, v149, v77 row_shr:1 row_mask:0xf bank_mask:0xf bound_ctrl:1
	v_exp_f32_e32 v248, v248
	v_fmac_f32_dpp v218, v86, v14 row_shr:2 row_mask:0xf bank_mask:0xf bound_ctrl:1
	v_exp_f32_e32 v249, v249
	v_fmac_f32_dpp v219, v87, v15 row_shr:2 row_mask:0xf bank_mask:0xf bound_ctrl:1
	v_pk_add_f32 v[242:243], v[242:243], s[92:93]
	v_fmac_f32_dpp v220, v88, v16 row_shr:2 row_mask:0xf bank_mask:0xf bound_ctrl:1
	v_pk_add_f32 v[244:245], v[244:245], s[92:93]
	v_fmac_f32_dpp v221, v89, v17 row_shr:2 row_mask:0xf bank_mask:0xf bound_ctrl:1
	v_pk_add_f32 v[246:247], v[246:247], s[92:93]
	v_fmac_f32_dpp v222, v146, v22 row_shr:2 row_mask:0xf bank_mask:0xf bound_ctrl:1
	v_pk_add_f32 v[248:249], v[248:249], s[92:93]
	v_fmac_f32_dpp v223, v147, v23 row_shr:2 row_mask:0xf bank_mask:0xf bound_ctrl:1
	v_rcp_f32_e32 v242, v242
	v_fmac_f32_dpp v224, v148, v24 row_shr:2 row_mask:0xf bank_mask:0xf bound_ctrl:1
	v_rcp_f32_e32 v243, v243
	v_fmac_f32_dpp v225, v149, v25 row_shr:2 row_mask:0xf bank_mask:0xf bound_ctrl:1
	v_rcp_f32_e32 v244, v244
	v_fmac_f32_dpp v218, v42, v154 row_ror:1 row_mask:0xf bank_mask:0xf bound_ctrl:1
	v_rcp_f32_e32 v245, v245
	v_fmac_f32_dpp v219, v43, v155 row_ror:1 row_mask:0xf bank_mask:0xf bound_ctrl:1
	v_rcp_f32_e32 v246, v246
	v_fmac_f32_dpp v220, v44, v156 row_ror:1 row_mask:0xf bank_mask:0xf bound_ctrl:1
	v_rcp_f32_e32 v247, v247
	v_fmac_f32_dpp v221, v45, v157 row_ror:1 row_mask:0xf bank_mask:0xf bound_ctrl:1
	v_rcp_f32_e32 v248, v248
	v_fmac_f32_dpp v222, v38, v158 row_ror:1 row_mask:0xf bank_mask:0xf bound_ctrl:1
	v_rcp_f32_e32 v249, v249
	v_fmac_f32_dpp v223, v39, v159 row_ror:1 row_mask:0xf bank_mask:0xf bound_ctrl:1
	v_pk_mul_f32 v[202:203], v[202:203], v[242:243]
	v_fmac_f32_dpp v224, v40, v160 row_ror:1 row_mask:0xf bank_mask:0xf bound_ctrl:1
	v_pk_mul_f32 v[204:205], v[204:205], v[244:245]
	v_fmac_f32_dpp v225, v41, v161 row_ror:1 row_mask:0xf bank_mask:0xf bound_ctrl:1
	v_pk_mul_f32 v[206:207], v[206:207], v[246:247]
	v_fmac_f32_dpp v218, v42, v182 row_ror:2 row_mask:0xf bank_mask:0xf bound_ctrl:1
	v_pk_mul_f32 v[226:227], v[226:227], v[248:249]
	v_fmac_f32_dpp v219, v43, v183 row_ror:2 row_mask:0xf bank_mask:0xf bound_ctrl:1
	v_pk_mul_f32 v[18:19], v[18:19], v[202:203]
	v_fmac_f32_dpp v220, v44, v184 row_ror:2 row_mask:0xf bank_mask:0xf bound_ctrl:1
	v_pk_mul_f32 v[20:21], v[20:21], v[204:205]
	v_fmac_f32_dpp v221, v45, v185 row_ror:2 row_mask:0xf bank_mask:0xf bound_ctrl:1
	v_pk_mul_f32 v[10:11], v[10:11], v[206:207]
	v_fmac_f32_dpp v222, v38, v190 row_ror:2 row_mask:0xf bank_mask:0xf bound_ctrl:1
	v_pk_mul_f32 v[12:13], v[12:13], v[226:227]
	v_fmac_f32_dpp v223, v39, v191 row_ror:2 row_mask:0xf bank_mask:0xf bound_ctrl:1
	v_cvt_pk_bf16_f32 v250, v18, v19
	v_fmac_f32_dpp v224, v40, v192 row_ror:2 row_mask:0xf bank_mask:0xf bound_ctrl:1
	v_cvt_pk_bf16_f32 v251, v20, v21
	v_fmac_f32_dpp v225, v41, v193 row_ror:2 row_mask:0xf bank_mask:0xf bound_ctrl:1
	v_cvt_pk_bf16_f32 v252, v10, v11
	v_cvt_pk_bf16_f32 v253, v12, v13
	global_store_dwordx4 v175, v[250:253], s[72:73]
	s_add_u32 s72, s84, 0xf2000
	s_addc_u32 s73, s85, 0
	v_pk_mul_f32 v[242:243], v[218:219], s[98:99]
	v_pk_mul_f32 v[244:245], v[220:221], s[98:99]
	v_pk_mul_f32 v[246:247], v[222:223], s[98:99]
	v_pk_mul_f32 v[248:249], v[224:225], s[98:99]
	v_exp_f32_e32 v242, v242
	v_exp_f32_e32 v243, v243
	v_exp_f32_e32 v244, v244
	v_exp_f32_e32 v245, v245
	v_exp_f32_e32 v246, v246
	v_exp_f32_e32 v247, v247
	v_exp_f32_e32 v248, v248
	v_exp_f32_e32 v249, v249
	v_pk_add_f32 v[242:243], v[242:243], s[92:93]
	v_pk_add_f32 v[244:245], v[244:245], s[92:93]
	v_pk_add_f32 v[246:247], v[246:247], s[92:93]
	v_pk_add_f32 v[248:249], v[248:249], s[92:93]
	v_rcp_f32_e32 v242, v242
	v_rcp_f32_e32 v243, v243
	v_rcp_f32_e32 v244, v244
	v_rcp_f32_e32 v245, v245
	v_rcp_f32_e32 v246, v246
	v_rcp_f32_e32 v247, v247
	v_rcp_f32_e32 v248, v248
	v_rcp_f32_e32 v249, v249
	v_pk_mul_f32 v[218:219], v[218:219], v[242:243]
	v_pk_mul_f32 v[220:221], v[220:221], v[244:245]
	v_pk_mul_f32 v[222:223], v[222:223], v[246:247]
	v_pk_mul_f32 v[224:225], v[224:225], v[248:249]
	v_pk_mul_f32 v[6:7], v[6:7], v[218:219]
	v_pk_mul_f32 v[8:9], v[8:9], v[220:221]
	v_pk_mul_f32 v[2:3], v[2:3], v[222:223]
	v_pk_mul_f32 v[4:5], v[4:5], v[224:225]
	v_cvt_pk_bf16_f32 v250, v6, v7
	v_cvt_pk_bf16_f32 v251, v8, v9
	v_cvt_pk_bf16_f32 v252, v2, v3
	v_cvt_pk_bf16_f32 v253, v4, v5
	global_store_dwordx4 v175, v[250:253], s[72:73]
	s_setprio 0
	s_andn2_b64 vcc, exec, s[38:39]
	s_mov_b64 s[38:39], -1
	s_cbranch_vccnz .LBB0_239
	s_andn2_b64 vcc, exec, s[62:63]
	s_cbranch_vccnz .LBB0_238
	s_barrier
	s_branch .LBB0_238
